# attnA: first key tile of each sequence peeled (m, l, O taken directly, no zero-init, no rescale)
# baseline (speedup 1.0000x reference)
; __device__ __forceinline__ void attnA_unit(const Args& a, int unit, LAS unsigned char* lds) {
;     ...
;         for (int e = 0; e < 2; ++e) {
;             const int qt = 2 * wid + e, r = qt % dl, i0 = (512 * blk) / dl + 32 * (qt / dl);
;             const int tq = dl * (i0 + ql) + r;
;             bf16x8 qf[4];
;             { const bf16_t* qp = P + ((size_t)b * SEQ + tq) * PW + 64 * hh + 8 * h;
; #pragma unroll
;               for (int s = 0; s < 4; ++s) qf[s] = *(const bf16x8*)(qp + 16 * s); }
;             f32x16 o0, o1;
; #pragma unroll
;             for (int i = 0; i < 16; ++i) { o0[i] = 0.f; o1[i] = 0.f; }
;             float m = -1e30f, l = 0.f;
;             int kt0 = 0, kt1 = 4;
;             if (i0 - 64 < 0) kt0 = (i0 - 32 < 0) ? 2 : 1;
;             if (i0 + 64 >= Ls) kt1 = (i0 + 32 >= Ls) ? 2 : 3;
;             const unsigned pitch = (unsigned)dl * (PW * 2);
;             u32x4 pk[4], pv[4];
;             { const size_t ro = (size_t)(dl * (i0 - 64 + 32 * kt0) + r) * (PW * 2); gload32(pk, kbase + ro, pitch, lane); gload32(pv, vbase + ro, pitch, lane); }
; #pragma unroll 1
;             for (int kt = kt0; kt <= kt1; ++kt) {
;                 asm volatile("" ::: "memory");
;                 lwrite32<true>(wl, pk, lane); lwrite32<false>(wl + 4096, pv, lane);
;                 if (kt < kt1) { const size_t ro = (size_t)(dl * (i0 - 64 + 32 * (kt + 1)) + r) * (PW * 2); gload32(pk, kbase + ro, pitch, lane); gload32(pv, vbase + ro, pitch, lane); }
;                 asm volatile("s_waitcnt lgkmcnt(0)" ::: "memory");
;                 bf16x8 kf[4], vf[2][2];
;                 load_kf(wl, kf, lane); load_vf(wl + 4096, vf, lane);
;                 attn_step<false>(kf, wl, vf, qf, o0, o1, m, l, lane, kt == 0 ? 1 : (kt == 4 ? 2 : 0));
.LaT_pass:
	s_or_b32 s0, s83, 0
	s_add_i32 s1, s72, -1
	s_and_b32 s74, s0, s1
	s_lshr_b32 s0, s0, s73
	s_lshl_b32 s0, s0, 5
	s_add_i32 s0, s0, s96
	v_add_u32_e32 v122, s0, v124
	v_lshlrev_b32_e32 v122, s73, v122
	v_add_u32_e32 v122, s74, v122
	v_add_u32_e32 v122, s76, v122
	v_mov_b32_e32 v123, 0
	v_add_u32_e32 v142, s0, v125
	v_lshlrev_b32_e32 v142, s73, v142
	v_add_u32_e32 v142, s74, v142
	v_add_u32_e32 v142, s76, v142
	s_movk_i32 s1, 0x1400
	v_mad_u64_u32 v[156:157], s[98:99], v122, s1, v[112:113]
	global_load_dwordx4 v[48:51], v[156:157], off
	global_load_dwordx4 v[52:55], v[156:157], off offset:32
	global_load_dwordx4 v[56:59], v[156:157], off offset:64
	global_load_dwordx4 v[60:63], v[156:157], off offset:96
	s_cmp_lt_i32 s0, 32
	s_cselect_b32 s1, 2, 1
	s_cmp_lt_i32 s0, 64
	s_cselect_b32 s86, s1, 0
	s_cmp_lt_i32 s0, s33
	s_cselect_b32 s1, 3, 2
	s_cmp_ge_i32 s0, s97
	s_cselect_b32 s87, s1, 4
	s_lshl_b32 s1, s86, 5
	s_add_i32 s0, s0, s1
	s_sub_i32 s75, s0, 64
	s_lshl_b32 s0, s75, s73
	s_add_i32 s0, s0, s74
	s_lshl_b32 s32, s83, 13
	s_mul_i32 s1, s0, 0x1400
	v_readlane_b32 s98, v255, 38
	v_readlane_b32 s99, v255, 39
	s_add_u32 s98, s98, s1
	s_addc_u32 s99, s99, 0
	s_sub_i32 s1, s92, 0x400
	s_mov_b32 m0, s32
	s_nop 0
	global_load_lds_dwordx4 v143, s[98:99]
	s_add_u32 s98, s98, s1
	s_addc_u32 s99, s99, 0
	global_load_lds_dwordx4 v144, s[98:99] offset:1024
	s_add_u32 s98, s98, s1
	s_addc_u32 s99, s99, 0
	global_load_lds_dwordx4 v143, s[98:99] offset:2048
	s_add_u32 s98, s98, s1
	s_addc_u32 s99, s99, 0
	global_load_lds_dwordx4 v144, s[98:99] offset:3072
	s_add_u32 s98, s98, 0x300
	s_addc_u32 s99, s99, 0
	s_add_i32 m0, s32, 0x1000
	s_nop 0
	global_load_lds_dwordx4 v145, s[98:99] offset:3072
	s_sub_u32 s98, s98, s1
	s_subb_u32 s99, s99, 0
	global_load_lds_dwordx4 v145, s[98:99] offset:2048
	s_sub_u32 s98, s98, s1
	s_subb_u32 s99, s99, 0
	global_load_lds_dwordx4 v145, s[98:99] offset:1024
	s_sub_u32 s98, s98, s1
	s_subb_u32 s99, s99, 0
	global_load_lds_dwordx4 v145, s[98:99]
	s_xor_b32 s32, s32, 0x2000
	s_add_i32 s75, s75, 32
	s_or_b32 s0, s83, 1
	s_add_i32 s1, s72, -1
	s_and_b32 s81, s0, s1
	s_lshr_b32 s0, s0, s73
	s_lshl_b32 s0, s0, 5
	s_add_i32 s0, s0, s96
	v_add_u32_e32 v216, s0, v124
	v_lshlrev_b32_e32 v216, s73, v216
	v_add_u32_e32 v216, s81, v216
	v_add_u32_e32 v216, s76, v216
	v_mov_b32_e32 v217, 0
	v_add_u32_e32 v224, s0, v125
	v_lshlrev_b32_e32 v224, s73, v224
	v_add_u32_e32 v224, s81, v224
	v_add_u32_e32 v224, s76, v224
	s_movk_i32 s1, 0x1400
	v_mad_u64_u32 v[156:157], s[98:99], v216, s1, v[112:113]
	global_load_dwordx4 v[196:199], v[156:157], off
	global_load_dwordx4 v[200:203], v[156:157], off offset:32
	global_load_dwordx4 v[204:207], v[156:157], off offset:64
	global_load_dwordx4 v[208:211], v[156:157], off offset:96
	s_cmp_lt_i32 s0, 32
	s_cselect_b32 s1, 2, 1
	s_cmp_lt_i32 s0, 64
	s_cselect_b32 s2, s1, 0
	s_cmp_lt_i32 s0, s33
	s_cselect_b32 s1, 3, 2
	s_cmp_ge_i32 s0, s97
	s_cselect_b32 s3, s1, 4
	s_lshl_b32 s1, s2, 5
	s_add_i32 s0, s0, s1
	s_sub_i32 s80, s0, 64
	s_lshl_b32 s0, s80, s73
	s_add_i32 s0, s0, s81
	s_lshl_b32 s32, s83, 13
	s_add_i32 s32, s32, 0x2000
	s_mul_i32 s1, s0, 0x1400
	v_readlane_b32 s98, v255, 38
	v_readlane_b32 s99, v255, 39
	s_add_u32 s98, s98, s1
	s_addc_u32 s99, s99, 0
	s_sub_i32 s1, s92, 0x400
	s_mov_b32 m0, s32
	s_nop 0
	global_load_lds_dwordx4 v143, s[98:99]
	s_add_u32 s98, s98, s1
	s_addc_u32 s99, s99, 0
	global_load_lds_dwordx4 v144, s[98:99] offset:1024
	s_add_u32 s98, s98, s1
	s_addc_u32 s99, s99, 0
	global_load_lds_dwordx4 v143, s[98:99] offset:2048
	s_add_u32 s98, s98, s1
	s_addc_u32 s99, s99, 0
	global_load_lds_dwordx4 v144, s[98:99] offset:3072
	s_add_u32 s98, s98, 0x300
	s_addc_u32 s99, s99, 0
	s_add_i32 m0, s32, 0x1000
	s_nop 0
	global_load_lds_dwordx4 v145, s[98:99] offset:3072
	s_sub_u32 s98, s98, s1
	s_subb_u32 s99, s99, 0
	global_load_lds_dwordx4 v145, s[98:99] offset:2048
	s_sub_u32 s98, s98, s1
	s_subb_u32 s99, s99, 0
	global_load_lds_dwordx4 v145, s[98:99] offset:1024
	s_sub_u32 s98, s98, s1
	s_subb_u32 s99, s99, 0
	global_load_lds_dwordx4 v145, s[98:99]
	s_xor_b32 s32, s32, 0x2000
	s_add_i32 s80, s80, 32
	s_waitcnt vmcnt(0)
	ds_read_b128 v[160:163], v130
	ds_read_b128 v[164:167], v131
	ds_read_b128 v[168:171], v132
	ds_read_b128 v[172:175], v133
	ds_read_b128 v[176:179], v130 offset:8192
	ds_read_b128 v[180:183], v131 offset:8192
	ds_read_b128 v[184:187], v132 offset:8192
	ds_read_b128 v[188:191], v133 offset:8192
	s_waitcnt lgkmcnt(7)
	v_mfma_f32_32x32x16_bf16 v[32:47], v[160:163], v[48:51], 0
	s_waitcnt lgkmcnt(3)
	v_mfma_f32_32x32x16_bf16 v[96:111], v[176:179], v[196:199], 0
	s_waitcnt lgkmcnt(6)
	v_mfma_f32_32x32x16_bf16 v[32:47], v[164:167], v[52:55], v[32:47]
	s_waitcnt lgkmcnt(2)
	v_mfma_f32_32x32x16_bf16 v[96:111], v[180:183], v[200:203], v[96:111]
	s_waitcnt lgkmcnt(5)
	v_mfma_f32_32x32x16_bf16 v[32:47], v[168:171], v[56:59], v[32:47]
	s_waitcnt lgkmcnt(1)
	v_mfma_f32_32x32x16_bf16 v[96:111], v[184:187], v[204:207], v[96:111]
	s_waitcnt lgkmcnt(4)
	v_mfma_f32_32x32x16_bf16 v[32:47], v[172:175], v[60:63], v[32:47]
	s_waitcnt lgkmcnt(0)
	v_mfma_f32_32x32x16_bf16 v[96:111], v[188:191], v[208:211], v[96:111]
	ds_read_b64_tr_b16 v[160:161], v134 offset:4096
	ds_read_b64_tr_b16 v[162:163], v134 offset:5120
	ds_read_b64_tr_b16 v[164:165], v134 offset:4160
	ds_read_b64_tr_b16 v[166:167], v134 offset:5184
	ds_read_b64_tr_b16 v[168:169], v134 offset:6144
	ds_read_b64_tr_b16 v[170:171], v134 offset:7168
	ds_read_b64_tr_b16 v[172:173], v134 offset:6208
	ds_read_b64_tr_b16 v[174:175], v134 offset:7232
	ds_read_b64_tr_b16 v[176:177], v134 offset:12288
	ds_read_b64_tr_b16 v[178:179], v134 offset:13312
	ds_read_b64_tr_b16 v[180:181], v134 offset:12352
	ds_read_b64_tr_b16 v[182:183], v134 offset:13376
	ds_read_b64_tr_b16 v[184:185], v134 offset:14336
	ds_read_b64_tr_b16 v[186:187], v134 offset:15360
	ds_read_b64_tr_b16 v[188:189], v134 offset:14400
	ds_read_b64_tr_b16 v[190:191], v134 offset:15424
	s_nop 7
	s_cmp_gt_u32 s86, s87
	s_cbranch_scc1 .LaT_m3aF
	s_cmp_eq_u32 s86, 0
	s_cbranch_scc1 .LaT_m1aF
	s_cmp_eq_u32 s86, 4
	s_cbranch_scc0 .LaT_m0aF
	v_cndmask_b32_e64 v32, v237, v32, s[6:7]
	v_cndmask_b32_e64 v33, v237, v33, s[10:11]
	v_cndmask_b32_e64 v34, v237, v34, s[14:15]
	v_cndmask_b32_e64 v35, v237, v35, s[18:19]
	v_cndmask_b32_e64 v36, v237, v36, s[22:23]
	v_cndmask_b32_e64 v37, v237, v37, s[26:27]
	v_cndmask_b32_e64 v38, v237, v38, s[30:31]
	v_cndmask_b32_e64 v39, v237, v39, s[36:37]
	v_cndmask_b32_e64 v40, v237, v40, s[40:41]
	v_cndmask_b32_e64 v41, v237, v41, s[44:45]
	v_cndmask_b32_e64 v42, v237, v42, s[48:49]
	v_cndmask_b32_e64 v43, v237, v43, s[52:53]
	v_cndmask_b32_e64 v44, v237, v44, s[56:57]
	v_cndmask_b32_e64 v45, v237, v45, s[60:61]
	v_cndmask_b32_e64 v46, v237, v46, s[64:65]
	v_cndmask_b32_e64 v47, v237, v47, s[68:69]
	s_branch .LaT_m0aF

; __device__ __forceinline__ unsigned pk2n(float lo, float hi) { const f32x2v v = {lo, hi}; const bf16v2 b = __builtin_convertvector(v, bf16v2); return __builtin_bit_cast(unsigned, b); }
; __device__ __forceinline__ float fexp2(float x) { return __builtin_amdgcn_exp2f(x); }
; template <bool KLDS>
; __device__ __forceinline__ void attn_step(const bf16x8 (&kf)[4], LAS const unsigned char* kb, const bf16x8 (&vf)[2][2], const bf16x8 (&qf)[4], f32x16& o0, f32x16& o1, float& m, float& l, int lane, int maskmode) {
;     ...
;     float tm = S[0];
; #pragma unroll
;     for (int i = 1; i < 16; ++i) tm = fmaxf(tm, S[i]);
;     tm = fmaxf(tm, __shfl_xor(tm, 32));
;     const float mn = fmaxf(m, tm), al = fexp2(m - mn); m = mn;
;     float ps = 0.f;
; #pragma unroll
;     for (int i = 0; i < 16; ++i) { S[i] = fexp2(S[i] - mn); ps += S[i]; }
;     l = l * al + ps;
; #pragma unroll
;     for (int i = 0; i < 16; ++i) { o0[i] *= al; o1[i] *= al; }
;     bf16x8 pf[2];
; #pragma unroll
;     for (int s2 = 0; s2 < 2; ++s2) {
;         u32x4 w; w.x = pk2n(S[8 * s2 + 0], S[8 * s2 + 1]); w.y = pk2n(S[8 * s2 + 2], S[8 * s2 + 3]); w.z = pk2n(S[8 * s2 + 4], S[8 * s2 + 5]); w.w = pk2n(S[8 * s2 + 6], S[8 * s2 + 7]);
;         pf[s2] = __builtin_bit_cast(bf16x8, w);
;     }
; #pragma unroll
;     for (int s2 = 0; s2 < 2; ++s2) {
;         o0 = __builtin_amdgcn_mfma_f32_32x32x16_bf16(vf[s2][0], pf[s2], o0, 0, 0, 0);
;         o1 = __builtin_amdgcn_mfma_f32_32x32x16_bf16(vf[s2][1], pf[s2], o1, 0, 0, 0);
;     }
.LaT_ndbF:
	s_add_i32 s80, s80, 32
	v_max3_f32 v138, v32, v33, v34
	v_max3_f32 v148, v96, v97, v98
	v_max3_f32 v138, v138, v35, v36
	v_max3_f32 v148, v148, v99, v100
	v_max3_f32 v138, v138, v37, v38
	v_max3_f32 v148, v148, v101, v102
	v_max3_f32 v138, v138, v39, v40
	v_max3_f32 v148, v148, v103, v104
	v_max3_f32 v138, v138, v41, v42
	v_max3_f32 v148, v148, v105, v106
	v_max3_f32 v138, v138, v43, v44
	v_max3_f32 v148, v148, v107, v108
	v_max3_f32 v138, v138, v45, v46
	v_max3_f32 v148, v148, v109, v110
	v_max_f32_e32 v138, v138, v47
	v_max_f32_e32 v148, v148, v111
	v_mov_b32_e32 v139, v138
	v_mov_b32_e32 v149, v148
	s_nop 1
	s_nop 1
	v_permlane32_swap_b32_e32 v139, v138
	v_permlane32_swap_b32_e32 v149, v148
	v_max_f32_e32 v137, v138, v139
	v_max_f32_e32 v212, v148, v149
	v_sub_f32_e32 v32, v32, v137
	v_sub_f32_e32 v96, v96, v212
	v_sub_f32_e32 v33, v33, v137
	v_sub_f32_e32 v97, v97, v212
	v_sub_f32_e32 v34, v34, v137
	v_sub_f32_e32 v98, v98, v212
	v_sub_f32_e32 v35, v35, v137
	v_sub_f32_e32 v99, v99, v212
	v_sub_f32_e32 v36, v36, v137
	v_sub_f32_e32 v100, v100, v212
	v_sub_f32_e32 v37, v37, v137
	v_sub_f32_e32 v101, v101, v212
	v_sub_f32_e32 v38, v38, v137
	v_sub_f32_e32 v102, v102, v212
	v_sub_f32_e32 v39, v39, v137
	v_sub_f32_e32 v103, v103, v212
	v_sub_f32_e32 v40, v40, v137
	v_sub_f32_e32 v104, v104, v212
	v_sub_f32_e32 v41, v41, v137
	v_sub_f32_e32 v105, v105, v212
	v_sub_f32_e32 v42, v42, v137
	v_sub_f32_e32 v106, v106, v212
	v_sub_f32_e32 v43, v43, v137
	v_sub_f32_e32 v107, v107, v212
	v_sub_f32_e32 v44, v44, v137
	v_sub_f32_e32 v108, v108, v212
	v_sub_f32_e32 v45, v45, v137
	v_sub_f32_e32 v109, v109, v212
	v_sub_f32_e32 v46, v46, v137
	v_sub_f32_e32 v110, v110, v212
	v_sub_f32_e32 v47, v47, v137
	v_sub_f32_e32 v111, v111, v212
	v_exp_f32_e32 v32, v32
	v_exp_f32_e32 v96, v96
	v_exp_f32_e32 v33, v33
	v_exp_f32_e32 v97, v97
	v_exp_f32_e32 v34, v34
	v_exp_f32_e32 v98, v98
	v_add_f32_e32 v152, v32, v33
	v_add_f32_e32 v218, v96, v97
	v_exp_f32_e32 v35, v35
	v_exp_f32_e32 v99, v99
	v_add_f32_e32 v153, v34, v35
	v_add_f32_e32 v219, v98, v99
	v_exp_f32_e32 v36, v36
	v_exp_f32_e32 v100, v100
	v_exp_f32_e32 v37, v37
	v_exp_f32_e32 v101, v101
	v_add_f32_e32 v153, v153, v36
	v_add_f32_e32 v219, v219, v100
	v_exp_f32_e32 v38, v38
	v_exp_f32_e32 v102, v102
	v_add_f32_e32 v152, v152, v37
	v_add_f32_e32 v218, v218, v101
	v_exp_f32_e32 v39, v39
	v_exp_f32_e32 v103, v103
	v_add_f32_e32 v153, v153, v38
	v_add_f32_e32 v219, v219, v102
	v_exp_f32_e32 v40, v40
	v_exp_f32_e32 v104, v104
	v_add_f32_e32 v152, v152, v39
	v_add_f32_e32 v218, v218, v103
	v_exp_f32_e32 v41, v41
	v_exp_f32_e32 v105, v105
	v_add_f32_e32 v153, v153, v40
	v_add_f32_e32 v219, v219, v104
	v_exp_f32_e32 v42, v42
	v_exp_f32_e32 v106, v106
	v_add_f32_e32 v152, v152, v41
	v_add_f32_e32 v218, v218, v105
	v_exp_f32_e32 v43, v43
	v_exp_f32_e32 v107, v107
	v_add_f32_e32 v153, v153, v42
	v_add_f32_e32 v219, v219, v106
	v_exp_f32_e32 v44, v44
	v_exp_f32_e32 v108, v108
	v_add_f32_e32 v152, v152, v43
	v_add_f32_e32 v218, v218, v107
	v_exp_f32_e32 v45, v45
	v_exp_f32_e32 v109, v109
	v_add_f32_e32 v153, v153, v44
	v_add_f32_e32 v219, v219, v108
	v_exp_f32_e32 v46, v46
	v_exp_f32_e32 v110, v110
	v_add_f32_e32 v152, v152, v45
	v_add_f32_e32 v218, v218, v109
	v_exp_f32_e32 v47, v47
	v_exp_f32_e32 v111, v111
	v_add_f32_e32 v153, v153, v46
	v_add_f32_e32 v219, v219, v110
	s_nop 0
	s_nop 0
	v_add_f32_e32 v153, v153, v47
	v_add_f32_e32 v219, v219, v111
	v_add_f32_e32 v135, v152, v153
	v_add_f32_e32 v213, v218, v219
	v_cvt_pk_bf16_f32 v32, v32, v33
	v_cvt_pk_bf16_f32 v96, v96, v97
	v_cvt_pk_bf16_f32 v33, v34, v35
	v_cvt_pk_bf16_f32 v97, v98, v99
	v_cvt_pk_bf16_f32 v34, v36, v37
	v_cvt_pk_bf16_f32 v98, v100, v101
	v_cvt_pk_bf16_f32 v35, v38, v39
	v_cvt_pk_bf16_f32 v99, v102, v103
	v_cvt_pk_bf16_f32 v36, v40, v41
	v_cvt_pk_bf16_f32 v100, v104, v105
	v_cvt_pk_bf16_f32 v37, v42, v43
	v_cvt_pk_bf16_f32 v101, v106, v107
	v_cvt_pk_bf16_f32 v38, v44, v45
	v_cvt_pk_bf16_f32 v102, v108, v109
	v_cvt_pk_bf16_f32 v39, v46, v47
	v_cvt_pk_bf16_f32 v103, v110, v111
	s_nop 0
	v_mfma_f32_32x32x16_bf16 v[16:31], v[160:163], v[32:35], 0
	v_mfma_f32_32x32x16_bf16 v[80:95], v[176:179], v[96:99], 0
	v_mfma_f32_32x32x16_bf16 v[0:15], v[164:167], v[32:35], 0
	v_mfma_f32_32x32x16_bf16 v[64:79], v[180:183], v[96:99], 0
	v_mfma_f32_32x32x16_bf16 v[16:31], v[168:171], v[36:39], v[16:31]
	v_mfma_f32_32x32x16_bf16 v[80:95], v[184:187], v[100:103], v[80:95]
	v_mfma_f32_32x32x16_bf16 v[0:15], v[172:175], v[36:39], v[0:15]
	v_mfma_f32_32x32x16_bf16 v[64:79], v[188:191], v[100:103], v[64:79]
	s_add_i32 s86, s86, 1
	s_add_i32 s2, s2, 1
